# attention queues: the FoX (batch, head) streams of an XCD taken one at a time (64 q-blocks of one stream, then the next)
# speedup vs baseline: 1.0134x; 1.0134x over previous
.LBB0_835:
	s_or_b64 exec, exec, s[0:1]
	s_waitcnt lgkmcnt(0)
	s_barrier
	ds_read_b32 v0, v202
	s_movk_i32 s0, 0x20b
	s_waitcnt lgkmcnt(0)
	s_barrier
	v_cmp_lt_i32_e32 vcc, s0, v0
	v_readfirstlane_b32 s54, v0
	s_mov_b64 s[0:1], -1
	s_cbranch_vccnz .LBB0_830
	s_cmp_lt_i32 s54, 8
	s_cbranch_scc1 .LBB0_846
	s_mov_b64 s[36:37], -1
	s_cmp_gt_u32 s54, 11
	s_mov_b64 s[38:39], -1
	s_cbranch_scc0 .LBB0_843
	s_mov_b64 s[4:5], -1
	s_cmpk_gt_u32 s54, 0x10b
	s_cbranch_scc0 .LBB0_840
	s_add_i32 s6, s54, 0xfffffef4
	s_lshr_b32 s30, s6, 6
	s_and_b32 s30, s30, 2
	s_add_i32 s30, s30, s70
	s_not_b32 s6, s6
	s_bfe_u32 s31, s6, 0x10006
	s_xor_b32 s31, s31, 1
	s_bfe_u32 s50, s6, 0x60000
	s_and_b32 s6, s30, 6
	s_lshr_b32 s55, s30, 3
	s_or_b32 s6, s6, s31
	s_mov_b64 s[38:39], 0
